# sample-row tasks of w_out/w_down GEMMs split 4-way along K over all 512 workgroups (f32 atomic accumulate onto the residual rows), deeper fragment-load rings; S^T tile relocated above 64 KB of LDS
# speedup vs baseline: 1.2426x; 1.0359x over previous
.LBB0_124:
.LBB0_125:
	v_readlane_b32 s4, v251, 6
	v_readlane_b32 s5, v251, 7
	v_readlane_b32 s6, v251, 20
	v_readlane_b32 s7, v251, 21
	v_readlane_b32 s8, v251, 18
	v_readlane_b32 s9, v251, 19
	s_cmp_ge_u32 s63, 0xa0
	s_cselect_b32 s10, 1, 0
	s_mul_i32 s11, s10, 0xa0
	s_sub_u32 s11, s63, s11
	s_add_u32 s4, s4, 0x2000000
	s_addc_u32 s5, s5, 0
	s_lshl_b32 s12, s11, 4
	s_mul_i32 s13, s12, 0x800
	s_lshl_b32 s14, s12, 2
	s_lshl_b32 s15, s10, 6
	v_and_b32_e32 v93, 63, v162
	v_lshrrev_b32_e32 v94, 6, v162
	v_and_b32_e32 v95, 15, v93
	v_lshrrev_b32_e32 v93, 4, v93
	v_lshl_add_u32 v94, v94, 4, s15
	v_add_u32_e32 v19, v94, v95
	v_mul_u32_u24_e32 v19, 0x800, v19
	v_lshl_add_u32 v19, v93, 5, v19
	v_mul_u32_u24_e32 v88, 0x800, v95
	v_lshl_add_u32 v88, v93, 5, v88
	v_add_u32_e32 v88, s13, v88
	v_lshl_add_u32 v94, v93, 2, v94
	v_mul_u32_u24_e32 v89, 0x2800, v94
	v_lshl_add_u32 v89, v95, 2, v89
	v_add_u32_e32 v89, s14, v89
	v_add_u32_e32 v90, 0x2800, v89
	v_add_u32_e32 v91, 0x2800, v90
	v_add_u32_e32 v92, 0x2800, v91
	v_mov_b32_e32 v20, 0
	v_mov_b32_e32 v21, 0
	v_mov_b32_e32 v22, 0
	v_mov_b32_e32 v23, 0
	global_load_dwordx4 v[24:27], v19, s[4:5] offset:0
	global_load_dwordx4 v[32:35], v88, s[6:7] offset:0
	global_load_dwordx4 v[28:31], v19, s[4:5] offset:16
	global_load_dwordx4 v[36:39], v88, s[6:7] offset:16
	global_load_dwordx4 v[40:43], v19, s[4:5] offset:128
	global_load_dwordx4 v[48:51], v88, s[6:7] offset:128
	global_load_dwordx4 v[44:47], v19, s[4:5] offset:144
	global_load_dwordx4 v[52:55], v88, s[6:7] offset:144
	global_load_dwordx4 v[56:59], v19, s[4:5] offset:256
	global_load_dwordx4 v[64:67], v88, s[6:7] offset:256
	global_load_dwordx4 v[60:63], v19, s[4:5] offset:272
	global_load_dwordx4 v[68:71], v88, s[6:7] offset:272
	global_load_dwordx4 v[72:75], v19, s[4:5] offset:384
	global_load_dwordx4 v[80:83], v88, s[6:7] offset:384
	global_load_dwordx4 v[76:79], v19, s[4:5] offset:400
	global_load_dwordx4 v[84:87], v88, s[6:7] offset:400
	global_load_dwordx4 v[104:107], v19, s[4:5] offset:512
	global_load_dwordx4 v[112:115], v88, s[6:7] offset:512
	global_load_dwordx4 v[108:111], v19, s[4:5] offset:528
	global_load_dwordx4 v[116:119], v88, s[6:7] offset:528
	global_load_dwordx4 v[120:123], v19, s[4:5] offset:640
	global_load_dwordx4 v[128:131], v88, s[6:7] offset:640
	global_load_dwordx4 v[124:127], v19, s[4:5] offset:656
	global_load_dwordx4 v[132:135], v88, s[6:7] offset:656
	global_load_dwordx4 v[140:143], v19, s[4:5] offset:768
	global_load_dwordx4 v[148:151], v88, s[6:7] offset:768
	global_load_dwordx4 v[144:147], v19, s[4:5] offset:784
	global_load_dwordx4 v[152:155], v88, s[6:7] offset:784
	s_waitcnt vmcnt(26)
	v_mfma_f32_16x16x32_bf16 v[20:23], v[24:27], v[32:35], v[20:23]
	s_waitcnt vmcnt(24)
	v_mfma_f32_16x16x32_bf16 v[20:23], v[28:31], v[36:39], v[20:23]
	s_nop 1
	global_load_dwordx4 v[24:27], v19, s[4:5] offset:896
	global_load_dwordx4 v[32:35], v88, s[6:7] offset:896
	global_load_dwordx4 v[28:31], v19, s[4:5] offset:912
	global_load_dwordx4 v[36:39], v88, s[6:7] offset:912
	s_waitcnt vmcnt(26)
	v_mfma_f32_16x16x32_bf16 v[20:23], v[40:43], v[48:51], v[20:23]
	s_waitcnt vmcnt(24)
	v_mfma_f32_16x16x32_bf16 v[20:23], v[44:47], v[52:55], v[20:23]
	s_nop 1
	global_load_dwordx4 v[40:43], v19, s[4:5] offset:1024
	global_load_dwordx4 v[48:51], v88, s[6:7] offset:1024
	global_load_dwordx4 v[44:47], v19, s[4:5] offset:1040
	global_load_dwordx4 v[52:55], v88, s[6:7] offset:1040
	s_waitcnt vmcnt(26)
	v_mfma_f32_16x16x32_bf16 v[20:23], v[56:59], v[64:67], v[20:23]
	s_waitcnt vmcnt(24)
	v_mfma_f32_16x16x32_bf16 v[20:23], v[60:63], v[68:71], v[20:23]
	s_nop 1
	global_load_dwordx4 v[56:59], v19, s[4:5] offset:1152
	global_load_dwordx4 v[64:67], v88, s[6:7] offset:1152
	global_load_dwordx4 v[60:63], v19, s[4:5] offset:1168
	global_load_dwordx4 v[68:71], v88, s[6:7] offset:1168
	s_waitcnt vmcnt(26)
	v_mfma_f32_16x16x32_bf16 v[20:23], v[72:75], v[80:83], v[20:23]
	s_waitcnt vmcnt(24)
	v_mfma_f32_16x16x32_bf16 v[20:23], v[76:79], v[84:87], v[20:23]
	s_nop 1
	global_load_dwordx4 v[72:75], v19, s[4:5] offset:1280
	global_load_dwordx4 v[80:83], v88, s[6:7] offset:1280
	global_load_dwordx4 v[76:79], v19, s[4:5] offset:1296
	global_load_dwordx4 v[84:87], v88, s[6:7] offset:1296
	s_waitcnt vmcnt(26)
	v_mfma_f32_16x16x32_bf16 v[20:23], v[104:107], v[112:115], v[20:23]
	s_waitcnt vmcnt(24)
	v_mfma_f32_16x16x32_bf16 v[20:23], v[108:111], v[116:119], v[20:23]
	s_nop 1
	global_load_dwordx4 v[104:107], v19, s[4:5] offset:1408
	global_load_dwordx4 v[112:115], v88, s[6:7] offset:1408
	global_load_dwordx4 v[108:111], v19, s[4:5] offset:1424
	global_load_dwordx4 v[116:119], v88, s[6:7] offset:1424
	s_waitcnt vmcnt(26)
	v_mfma_f32_16x16x32_bf16 v[20:23], v[120:123], v[128:131], v[20:23]
	s_waitcnt vmcnt(24)
	v_mfma_f32_16x16x32_bf16 v[20:23], v[124:127], v[132:135], v[20:23]
	s_nop 1
	global_load_dwordx4 v[120:123], v19, s[4:5] offset:1536
	global_load_dwordx4 v[128:131], v88, s[6:7] offset:1536
	global_load_dwordx4 v[124:127], v19, s[4:5] offset:1552
	global_load_dwordx4 v[132:135], v88, s[6:7] offset:1552
	s_waitcnt vmcnt(26)
	v_mfma_f32_16x16x32_bf16 v[20:23], v[140:143], v[148:151], v[20:23]
	s_waitcnt vmcnt(24)
	v_mfma_f32_16x16x32_bf16 v[20:23], v[144:147], v[152:155], v[20:23]
	s_nop 1
	global_load_dwordx4 v[140:143], v19, s[4:5] offset:1664
	global_load_dwordx4 v[148:151], v88, s[6:7] offset:1664
	global_load_dwordx4 v[144:147], v19, s[4:5] offset:1680
	global_load_dwordx4 v[152:155], v88, s[6:7] offset:1680
	s_waitcnt vmcnt(26)
	v_mfma_f32_16x16x32_bf16 v[20:23], v[24:27], v[32:35], v[20:23]
	s_waitcnt vmcnt(24)
	v_mfma_f32_16x16x32_bf16 v[20:23], v[28:31], v[36:39], v[20:23]
	s_nop 1
	global_load_dwordx4 v[24:27], v19, s[4:5] offset:1792
	global_load_dwordx4 v[32:35], v88, s[6:7] offset:1792
	global_load_dwordx4 v[28:31], v19, s[4:5] offset:1808
	global_load_dwordx4 v[36:39], v88, s[6:7] offset:1808
	s_waitcnt vmcnt(26)
	v_mfma_f32_16x16x32_bf16 v[20:23], v[40:43], v[48:51], v[20:23]
	s_waitcnt vmcnt(24)
	v_mfma_f32_16x16x32_bf16 v[20:23], v[44:47], v[52:55], v[20:23]
	s_nop 1
	global_load_dwordx4 v[40:43], v19, s[4:5] offset:1920
	global_load_dwordx4 v[48:51], v88, s[6:7] offset:1920
	global_load_dwordx4 v[44:47], v19, s[4:5] offset:1936
	global_load_dwordx4 v[52:55], v88, s[6:7] offset:1936
	s_waitcnt vmcnt(26)
	v_mfma_f32_16x16x32_bf16 v[20:23], v[56:59], v[64:67], v[20:23]
	s_waitcnt vmcnt(24)
	v_mfma_f32_16x16x32_bf16 v[20:23], v[60:63], v[68:71], v[20:23]
	s_waitcnt vmcnt(22)
	v_mfma_f32_16x16x32_bf16 v[20:23], v[72:75], v[80:83], v[20:23]
	s_waitcnt vmcnt(20)
	v_mfma_f32_16x16x32_bf16 v[20:23], v[76:79], v[84:87], v[20:23]
	s_waitcnt vmcnt(18)
	v_mfma_f32_16x16x32_bf16 v[20:23], v[104:107], v[112:115], v[20:23]
	s_waitcnt vmcnt(16)
	v_mfma_f32_16x16x32_bf16 v[20:23], v[108:111], v[116:119], v[20:23]
	s_waitcnt vmcnt(14)
	v_mfma_f32_16x16x32_bf16 v[20:23], v[120:123], v[128:131], v[20:23]
	s_waitcnt vmcnt(12)
	v_mfma_f32_16x16x32_bf16 v[20:23], v[124:127], v[132:135], v[20:23]
	s_waitcnt vmcnt(10)
	v_mfma_f32_16x16x32_bf16 v[20:23], v[140:143], v[148:151], v[20:23]
	s_waitcnt vmcnt(8)
	v_mfma_f32_16x16x32_bf16 v[20:23], v[144:147], v[152:155], v[20:23]
	s_waitcnt vmcnt(6)
	v_mfma_f32_16x16x32_bf16 v[20:23], v[24:27], v[32:35], v[20:23]
	s_waitcnt vmcnt(4)
	v_mfma_f32_16x16x32_bf16 v[20:23], v[28:31], v[36:39], v[20:23]
	s_waitcnt vmcnt(2)
	v_mfma_f32_16x16x32_bf16 v[20:23], v[40:43], v[48:51], v[20:23]
	s_waitcnt vmcnt(0)
	v_mfma_f32_16x16x32_bf16 v[20:23], v[44:47], v[52:55], v[20:23]
	s_nop 7
	s_nop 7
	global_store_dword v89, v20, s[8:9]
	global_store_dword v90, v21, s[8:9]
	global_store_dword v91, v22, s[8:9]
	global_store_dword v92, v23, s[8:9]
	s_branch .Lp1_task_done

.LBB0_550:
	s_andn2_b64 vcc, exec, s[0:1]
	s_cbranch_vccnz .LBB0_521
	s_mov_b64 s[0:1], 0
	v_add_u32_e32 v0, 0x10c00, v99
	v_mov_b32_e32 v1, v103
	s_barrier
.LBB0_552:
	v_add_u32_e32 v1, 0x100, v1
	s_movk_i32 s8, 0xfff
	v_cmp_lt_u32_e32 vcc, s8, v1
	ds_write_b16 v0, v113
	s_or_b64 s[0:1], vcc, s[0:1]
	v_add_u32_e32 v0, 0x200, v0
	s_andn2_b64 exec, exec, s[0:1]
	s_cbranch_execnz .LBB0_552
	s_or_b64 exec, exec, s[0:1]
	s_ashr_i32 s22, s24, 4
	s_bfe_u32 s25, s24, 0x20002
	s_lshl_b32 s0, s22, 2
	s_or_b32 s0, s0, s25
	s_lshl_b32 s18, s0, 5
	s_ashr_i32 s19, s18, 31
	s_mul_i32 s1, s0, 0x240000
	s_mul_hi_i32 s8, s18, 0x12000
	s_add_u32 s16, s30, s1
	s_addc_u32 s17, s31, s8
	v_mov_b32_e32 v143, v113
	v_lshl_add_u64 v[0:1], v[116:117], 1, s[16:17]
	s_lshl_b32 s1, s24, 5
	v_lshl_add_u64 v[0:1], v[0:1], 0, v[142:143]
	s_and_b32 s8, s1, 0x60
	v_add_co_u32_e32 v6, vcc, s26, v0
	s_waitcnt vmcnt(18)
	v_or_b32_e32 v22, s8, v98
	s_mov_b64 s[46:47], 0x4000
	v_addc_co_u32_e32 v7, vcc, 0, v1, vcc
	v_add_u32_e32 v112, v22, v173
	v_readlane_b32 s68, v251, 8
	v_lshl_add_u64 v[2:3], v[0:1], 0, s[46:47]
	v_lshl_add_u64 v[4:5], v[0:1], 0, s[10:11]
	v_add_co_u32_e32 v0, vcc, s42, v0
	v_or_b32_e32 v8, v22, v173
	v_lshlrev_b64 v[80:81], 1, v[112:113]
	v_readlane_b32 s72, v251, 12
	v_readlane_b32 s73, v251, 13
	v_addc_co_u32_e32 v1, vcc, 0, v1, vcc
	v_lshlrev_b32_e32 v36, 1, v8
	v_lshl_add_u64 v[8:9], s[16:17], 0, v[80:81]
	v_add_u32_e32 v56, v22, v174
	v_mov_b32_e32 v57, v113
	v_add_u32_e32 v58, v22, v175
	v_mov_b32_e32 v59, v113
	v_add_u32_e32 v112, v22, v176
	v_readlane_b32 s74, v251, 14
	v_readlane_b32 s75, v251, 15
	v_readlane_b32 s76, v251, 16
	v_readlane_b32 s77, v251, 17
	v_readlane_b32 s78, v251, 18
	v_readlane_b32 s79, v251, 19
	s_mov_b64 s[48:49], s[72:73]
	global_load_dwordx4 v[32:35], v[6:7], off
	global_load_dwordx4 v[44:47], v[0:1], off
	global_load_dwordx4 v[12:15], v[2:3], off offset:64
	global_load_dwordx4 v[16:19], v[2:3], off offset:128
	global_load_dwordx4 v[28:31], v[4:5], off offset:64
	s_nop 0
	global_load_dwordx4 v[0:3], v[2:3], off offset:192
	s_nop 0
	global_load_dwordx4 v[24:27], v[4:5], off offset:128
	s_nop 0
	global_load_dwordx4 v[4:7], v[4:5], off offset:192
	v_lshl_add_u64 v[10:11], v[56:57], 1, s[16:17]
	v_lshl_add_u64 v[20:21], v[58:59], 1, s[16:17]
	v_lshl_add_u64 v[22:23], v[112:113], 1, s[16:17]
	global_load_ushort v186, v36, s[16:17]
	global_load_ushort v188, v[8:9], off offset:256
	global_load_ushort v185, v[8:9], off offset:512
	global_load_ushort v89, v[8:9], off offset:768
	global_load_ushort v187, v[10:11], off offset:32
	global_load_ushort v189, v[20:21], off offset:32
	global_load_ushort v190, v[22:23], off offset:32
	global_load_ushort v91, v[8:9], off offset:32
	s_lshl_b64 s[18:19], s[18:19], 2
	s_mov_b64 s[52:53], s[76:77]
	v_lshl_add_u64 v[8:9], v[118:119], 1, s[16:17]
	s_add_u32 s46, s52, s18
	v_lshl_add_u64 v[8:9], v[8:9], 0, v[142:143]
	s_addc_u32 s47, s53, s19
	v_lshl_add_u64 v[10:11], v[8:9], 0, s[14:15]
	v_lshl_add_u64 v[20:21], s[16:17], 0, v[142:143]
	v_add_co_u32_e32 v8, vcc, s43, v8
	global_load_dword v88, v113, s[46:47]
	s_nop 0
	v_addc_co_u32_e32 v9, vcc, 0, v9, vcc
	v_lshl_add_u64 v[20:21], v[120:121], 1, v[20:21]
	s_mov_b64 s[46:47], 0xc000
	s_mov_b32 s1, 0xc000
	v_lshl_add_u64 v[22:23], v[20:21], 0, s[46:47]
	v_add_co_u32_e32 v20, vcc, s1, v20
	s_ashr_i32 s23, s22, 31
	s_nop 0
	v_addc_co_u32_e32 v21, vcc, 0, v21, vcc
	global_load_dwordx4 v[52:55], v[8:9], off
	global_load_dwordx4 v[48:51], v[10:11], off offset:64
	s_nop 0
	global_load_dwordx4 v[8:11], v[22:23], off offset:2048
	global_load_dwordx4 v[36:39], v[22:23], off offset:64
	global_load_dwordx4 v[40:43], v[20:21], off
	s_nop 0
	global_load_dwordx4 v[20:23], v[22:23], off offset:2112
	s_add_u32 s18, s3, s18
	s_addc_u32 s19, s4, s19
	s_lshl_b64 s[22:23], s[22:23], 22
	s_lshl_b32 s25, s25, 9
	s_and_b32 s24, s24, 3
	s_or_b32 s22, s22, s25
	s_lshl_b32 s24, s24, 7
	v_lshlrev_b32_e32 v84, 1, v56
	s_or_b32 s22, s22, s24
	v_mov_b32_e32 v56, 0
	s_mov_b32 s1, 0
	v_lshlrev_b32_e32 v112, 1, v112
	v_lshlrev_b32_e32 v82, 1, v58
	v_mov_b32_e32 v83, v113
	v_mov_b32_e32 v85, v113
	v_lshl_add_u64 v[86:87], v[140:141], 0, s[22:23]
	v_mov_b32_e32 v57, v56
	v_mov_b32_e32 v58, v56
	v_mov_b32_e32 v59, v56
	v_mov_b32_e32 v64, v56
	v_mov_b32_e32 v65, v56
	v_mov_b32_e32 v66, v56
	v_mov_b32_e32 v67, v56
	v_mov_b32_e32 v68, v56
	v_mov_b32_e32 v69, v56
	v_mov_b32_e32 v70, v56
	v_mov_b32_e32 v71, v56
	v_mov_b32_e32 v60, v56
	v_mov_b32_e32 v61, v56
	v_mov_b32_e32 v62, v56
	v_mov_b32_e32 v63, v56
	v_readlane_b32 s69, v251, 9
	v_readlane_b32 s70, v251, 10
	v_readlane_b32 s71, v251, 11
	v_readlane_b32 s80, v251, 20
	v_readlane_b32 s81, v251, 21
	v_readlane_b32 s82, v251, 22
	v_readlane_b32 s83, v251, 23
	s_mov_b64 s[50:51], s[74:75]
	s_mov_b64 s[54:55], s[78:79]
	s_waitcnt lgkmcnt(0)
	s_barrier
	v_and_b32_e32 v242, 63, v162
	v_lshrrev_b32_e32 v243, 6, v162
	v_and_b32_e32 v244, 15, v242
	v_lshrrev_b32_e32 v245, 4, v242
	v_readfirstlane_b32 s56, v243
	v_xor_b32_e32 v250, v244, v245
	v_lshlrev_b32_e32 v253, 12, v243
	v_lshl_add_u32 v253, v245, 8, v253
	v_add_u32_e32 v253, 0x4000, v253
	v_xor_b32_e32 v254, 0, v250
	v_lshl_add_u32 v204, v254, 4, v253
	v_xor_b32_e32 v254, 4, v250
	v_lshl_add_u32 v205, v254, 4, v253
	v_add_u32_e32 v205, 0x400, v205
	v_xor_b32_e32 v254, 8, v250
	v_lshl_add_u32 v206, v254, 4, v253
	v_add_u32_e32 v206, 0x800, v206
	v_xor_b32_e32 v254, 12, v250
	v_lshl_add_u32 v207, v254, 4, v253
	v_add_u32_e32 v207, 0xc00, v207
	v_lshrrev_b32_e32 v253, 3, v242
	v_and_b32_e32 v254, 7, v242
	v_xor_b32_e32 v254, v254, v253
	v_lshlrev_b32_e32 v254, 4, v254
	v_lshl_add_u32 v254, v253, 7, v254
	v_lshl_add_u32 v210, v243, 12, v254
	v_add_u32_e32 v210, 0xc000, v210
	v_lshl_add_u32 v211, v243, 11, v254
	v_add_u32_e32 v211, 0x10000, v211
	v_lshl_add_u32 v253, v243, 2, v245
	v_lshlrev_b32_e32 v212, 10, v253
	v_add_u32_e32 v254, s8, v244
	v_lshl_add_u32 v212, v254, 1, v212
	v_lshlrev_b32_e32 v253, 12, v243
	v_lshl_add_u32 v253, v244, 8, v253
	v_add_u32_e32 v253, 0x3400, v253
	v_xor_b32_e32 v254, 0, v250
	v_lshl_add_u32 v213, v254, 4, v253
	v_xor_b32_e32 v254, 4, v250
	v_lshl_add_u32 v214, v254, 4, v253
	v_xor_b32_e32 v254, 8, v250
	v_lshl_add_u32 v215, v254, 4, v253
	v_xor_b32_e32 v254, 12, v250
	v_lshl_add_u32 v216, v254, 4, v253
	v_and_b32_e32 v254, 7, v244
	v_xor_b32_e32 v250, v254, v245
	v_lshlrev_b32_e32 v253, 7, v244
	v_lshl_add_u32 v242, v243, 12, v253
	v_add_u32_e32 v242, 0xb400, v242
	v_lshl_add_u32 v253, v243, 11, v253
	v_add_u32_e32 v253, 0x0, v253
	v_xor_b32_e32 v254, 0, v250
	v_lshl_add_u32 v217, v254, 4, v242
	v_lshl_add_u32 v221, v254, 4, v253
	v_xor_b32_e32 v254, 4, v250
	v_lshl_add_u32 v220, v254, 4, v242
	v_lshl_add_u32 v222, v254, 4, v253
	v_mul_u32_u24_e32 v253, 0x110, v244
	v_add_u32_e32 v253, 0x10c00, v253
	v_lshl_add_u32 v246, v245, 4, v253
	v_lshl_add_u32 v249, v245, 3, v253
	v_lshl_add_u32 v249, v243, 6, v249
	v_mul_u32_u24_e32 v253, 0x90, v244
	v_add_u32_e32 v253, 0x2200, v253
	v_lshl_add_u32 v248, v245, 4, v253
	v_lshl_add_u32 v247, v245, 3, v253
	v_lshl_add_u32 v247, v243, 5, v247
	s_add_u32 s20, s16, 0x12000
	s_addc_u32 s21, s17, 0
	s_add_u32 s22, s20, 0x4000
	s_addc_u32 s23, s21, 0
	s_mov_b64 s[46:47], s[18:19]
	s_mov_b64 s[50:51], 0x20000
	s_lshl_b32 s52, s56, 12
	s_add_u32 s53, s52, 0x7400
	s_add_u32 s54, s52, 0xb400
	s_add_u32 s52, s52, 0x3400
	s_lshl_b32 s55, s56, 11
	s_add_u32 s55, s55, 0x0
	s_waitcnt vmcnt(15)
	ds_read_b128 v[148:151], v246 offset:0
	ds_read_b128 v[192:195], v246 offset:4352
	ds_read_b128 v[196:199], v246 offset:64
	ds_read_b128 v[200:203], v246 offset:4416
	s_waitcnt lgkmcnt(3)
	s_add_u32 m0, s52, 0x0
	v_mfma_f32_16x16x32_bf16 v[92:95], v[32:35], v[148:151], 0
	global_load_lds_dwordx4 v204, s[20:21]
	v_mfma_f32_16x16x32_bf16 v[72:75], v[148:151], v[44:47], 0
	s_waitcnt lgkmcnt(2)
	s_add_u32 m0, s52, 0x400
	v_mfma_f32_16x16x32_bf16 v[144:147], v[32:35], v[192:195], 0
	global_load_lds_dwordx4 v205, s[20:21]
	v_mfma_f32_16x16x32_bf16 v[76:79], v[192:195], v[44:47], 0
	ds_read_b128 v[148:151], v246 offset:128
	ds_read_b128 v[192:195], v246 offset:4480
	s_waitcnt lgkmcnt(3)
	s_add_u32 m0, s52, 0x800
	v_mfma_f32_16x16x32_bf16 v[92:95], v[12:15], v[196:199], v[92:95]
	global_load_lds_dwordx4 v206, s[20:21]
	v_mfma_f32_16x16x32_bf16 v[72:75], v[196:199], v[28:31], v[72:75]
	s_waitcnt lgkmcnt(2)
	s_add_u32 m0, s52, 0xc00
	v_mfma_f32_16x16x32_bf16 v[144:147], v[12:15], v[200:203], v[144:147]
	global_load_lds_dwordx4 v207, s[20:21]
	v_mfma_f32_16x16x32_bf16 v[76:79], v[200:203], v[28:31], v[76:79]
	ds_read_b128 v[196:199], v246 offset:192
	ds_read_b128 v[200:203], v246 offset:4544
	s_waitcnt lgkmcnt(3)
	s_add_u32 m0, s53, 0x0
	v_mfma_f32_16x16x32_bf16 v[92:95], v[16:19], v[148:151], v[92:95]
	global_load_lds_dwordx4 v204, s[22:23]
	v_mfma_f32_16x16x32_bf16 v[72:75], v[148:151], v[24:27], v[72:75]
	s_waitcnt lgkmcnt(2)
	s_add_u32 m0, s53, 0x400
	v_mfma_f32_16x16x32_bf16 v[144:147], v[16:19], v[192:195], v[144:147]
	global_load_lds_dwordx4 v205, s[22:23]
	v_mfma_f32_16x16x32_bf16 v[76:79], v[192:195], v[24:27], v[76:79]
	s_waitcnt lgkmcnt(1)
	s_add_u32 m0, s53, 0x800
	v_mfma_f32_16x16x32_bf16 v[92:95], v[0:3], v[196:199], v[92:95]
	global_load_lds_dwordx4 v206, s[22:23]
	v_mfma_f32_16x16x32_bf16 v[72:75], v[196:199], v[4:7], v[72:75]
	s_waitcnt lgkmcnt(0)
	s_add_u32 m0, s53, 0xc00
	v_mfma_f32_16x16x32_bf16 v[144:147], v[0:3], v[200:203], v[144:147]
	global_load_lds_dwordx4 v207, s[22:23]
	v_mfma_f32_16x16x32_bf16 v[76:79], v[200:203], v[4:7], v[76:79]
	s_waitcnt vmcnt(14)
	v_mov_b32_e32 v255, v88
	s_nop 7
	v_lshlrev_b32_e32 v242, 16, v186
	v_lshlrev_b32_e32 v243, 16, v188
	v_lshlrev_b32_e32 v244, 16, v185
	v_lshlrev_b32_e32 v245, 16, v89
	v_sub_f32_e32 v242, v242, v92
	v_sub_f32_e32 v243, v243, v93
	v_sub_f32_e32 v244, v244, v94
	v_sub_f32_e32 v245, v245, v95
	v_cvt_pk_bf16_f32 v242, v242, v243
	v_cvt_pk_bf16_f32 v243, v244, v245
	ds_write_b64 v247, v[242:243]
	v_lshlrev_b32_e32 v242, 16, v91
	v_lshlrev_b32_e32 v243, 16, v187
	v_lshlrev_b32_e32 v244, 16, v189
	v_lshlrev_b32_e32 v245, 16, v190
	v_sub_f32_e32 v242, v242, v144
	v_sub_f32_e32 v243, v243, v145
	v_sub_f32_e32 v244, v244, v146
	v_sub_f32_e32 v245, v245, v147
	v_cvt_pk_bf16_f32 v242, v242, v243
	v_cvt_pk_bf16_f32 v243, v244, v245
	ds_write_b64 v247, v[242:243] offset:2304
	global_load_ushort v186, v212, s[20:21] offset:0
	global_load_ushort v188, v212, s[20:21] offset:256
	global_load_ushort v185, v212, s[20:21] offset:512
	global_load_ushort v89, v212, s[20:21] offset:768
	global_load_ushort v91, v212, s[20:21] offset:32
	global_load_ushort v187, v212, s[20:21] offset:288
	global_load_ushort v189, v212, s[20:21] offset:544
	global_load_ushort v190, v212, s[20:21] offset:800
	global_load_dword v88, v113, s[46:47]
	s_waitcnt lgkmcnt(0)
	s_barrier
	s_waitcnt vmcnt(17)
	ds_read_b128 v[148:151], v248 offset:0
	ds_read_b128 v[192:195], v248 offset:2304
	ds_read_b128 v[196:199], v248 offset:64
	ds_read_b128 v[200:203], v248 offset:2368
	v_mul_f32_e32 v56, v56, v255
	v_mul_f32_e32 v57, v57, v255
	v_mul_f32_e32 v58, v58, v255
	v_mul_f32_e32 v59, v59, v255
	v_mul_f32_e32 v64, v64, v255
	v_mul_f32_e32 v65, v65, v255
	v_mul_f32_e32 v66, v66, v255
	v_mul_f32_e32 v67, v67, v255
	v_mul_f32_e32 v68, v68, v255
	v_mul_f32_e32 v69, v69, v255
	v_mul_f32_e32 v70, v70, v255
	v_mul_f32_e32 v71, v71, v255
	v_mul_f32_e32 v60, v60, v255
	v_mul_f32_e32 v61, v61, v255
	v_mul_f32_e32 v62, v62, v255
	v_mul_f32_e32 v63, v63, v255
	s_waitcnt lgkmcnt(3)
	v_mfma_f32_16x16x32_bf16 v[72:75], v[148:151], v[52:55], v[72:75]
	s_waitcnt lgkmcnt(2)
	v_mfma_f32_16x16x32_bf16 v[76:79], v[192:195], v[52:55], v[76:79]
	s_waitcnt lgkmcnt(1)
	v_mfma_f32_16x16x32_bf16 v[72:75], v[196:199], v[48:51], v[72:75]
	s_waitcnt lgkmcnt(0)
	v_mfma_f32_16x16x32_bf16 v[76:79], v[200:203], v[48:51], v[76:79]
	s_mov_b32 m0, s54
	v_mfma_f32_16x16x32_bf16 v[56:59], v[40:43], v[148:151], v[56:59]
	global_load_lds_dwordx4 v210, s[20:21]
	v_mfma_f32_16x16x32_bf16 v[64:67], v[40:43], v[192:195], v[64:67]
	v_mfma_f32_16x16x32_bf16 v[56:59], v[36:39], v[196:199], v[56:59]
	global_load_lds_dwordx4 v210, s[20:21] offset:1024
	v_mfma_f32_16x16x32_bf16 v[64:67], v[36:39], v[200:203], v[64:67]
	v_mfma_f32_16x16x32_bf16 v[68:71], v[8:11], v[148:151], v[68:71]
	global_load_lds_dwordx4 v210, s[20:21] offset:2048
	v_mfma_f32_16x16x32_bf16 v[60:63], v[8:11], v[192:195], v[60:63]
	v_mfma_f32_16x16x32_bf16 v[68:71], v[20:23], v[196:199], v[68:71]
	global_load_lds_dwordx4 v210, s[20:21] offset:3072
	v_mfma_f32_16x16x32_bf16 v[60:63], v[20:23], v[200:203], v[60:63]
	s_mov_b32 m0, s55
	s_nop 0
	global_load_lds_dwordx4 v211, s[20:21]
	s_nop 0
	global_load_lds_dwordx4 v211, s[20:21] offset:1024
	s_nop 3
	global_store_dwordx4 v[86:87], v[72:75], off
	global_store_dwordx4 v[86:87], v[76:79], off offset:64
	s_nop 7
	v_cvt_pk_bf16_f32 v242, v56, v57
	v_cvt_pk_bf16_f32 v243, v58, v59
	ds_write_b64 v249, v[242:243]
	v_cvt_pk_bf16_f32 v242, v64, v65
	v_cvt_pk_bf16_f32 v243, v66, v67
	ds_write_b64 v249, v[242:243] offset:4352
	v_cvt_pk_bf16_f32 v242, v68, v69
	v_cvt_pk_bf16_f32 v243, v70, v71
	ds_write_b64 v249, v[242:243] offset:32
	v_cvt_pk_bf16_f32 v242, v60, v61
	v_cvt_pk_bf16_f32 v243, v62, v63
	ds_write_b64 v249, v[242:243] offset:4384
	v_lshl_add_u64 v[86:87], v[86:87], 0, s[50:51]
	s_add_u32 s20, s20, 0x12000
	s_addc_u32 s21, s21, 0
	s_add_u32 s22, s22, 0x12000
	s_addc_u32 s23, s23, 0
	s_add_u32 s46, s46, 4
	s_addc_u32 s47, s47, 0
	s_waitcnt lgkmcnt(0)
	s_barrier
	s_waitcnt vmcnt(17)
	ds_read_b128 v[32:35], v213
	ds_read_b128 v[44:47], v213 offset:16384
	ds_read_b128 v[12:15], v214
	ds_read_b128 v[28:31], v214 offset:16384
	ds_read_b128 v[16:19], v215
	ds_read_b128 v[24:27], v215 offset:16384
	ds_read_b128 v[0:3], v216
	ds_read_b128 v[4:7], v216 offset:16384
	ds_read_b128 v[148:151], v246 offset:0
	ds_read_b128 v[192:195], v246 offset:4352
	ds_read_b128 v[196:199], v246 offset:64
	ds_read_b128 v[200:203], v246 offset:4416
	s_waitcnt lgkmcnt(4)
	s_waitcnt lgkmcnt(3)
	s_add_u32 m0, s52, 0x0
	v_mfma_f32_16x16x32_bf16 v[92:95], v[32:35], v[148:151], 0
	global_load_lds_dwordx4 v204, s[20:21]
	v_mfma_f32_16x16x32_bf16 v[72:75], v[148:151], v[44:47], 0
	s_waitcnt lgkmcnt(2)
	s_add_u32 m0, s52, 0x400
	v_mfma_f32_16x16x32_bf16 v[144:147], v[32:35], v[192:195], 0
	global_load_lds_dwordx4 v205, s[20:21]
	v_mfma_f32_16x16x32_bf16 v[76:79], v[192:195], v[44:47], 0
	ds_read_b128 v[148:151], v246 offset:128
	ds_read_b128 v[192:195], v246 offset:4480
	s_waitcnt lgkmcnt(3)
	s_add_u32 m0, s52, 0x800
	v_mfma_f32_16x16x32_bf16 v[92:95], v[12:15], v[196:199], v[92:95]
	global_load_lds_dwordx4 v206, s[20:21]
	v_mfma_f32_16x16x32_bf16 v[72:75], v[196:199], v[28:31], v[72:75]
	s_waitcnt lgkmcnt(2)
	s_add_u32 m0, s52, 0xc00
	v_mfma_f32_16x16x32_bf16 v[144:147], v[12:15], v[200:203], v[144:147]
	global_load_lds_dwordx4 v207, s[20:21]
	v_mfma_f32_16x16x32_bf16 v[76:79], v[200:203], v[28:31], v[76:79]
	ds_read_b128 v[196:199], v246 offset:192
	ds_read_b128 v[200:203], v246 offset:4544
	s_waitcnt lgkmcnt(3)
	s_add_u32 m0, s53, 0x0
	v_mfma_f32_16x16x32_bf16 v[92:95], v[16:19], v[148:151], v[92:95]
	global_load_lds_dwordx4 v204, s[22:23]
	v_mfma_f32_16x16x32_bf16 v[72:75], v[148:151], v[24:27], v[72:75]
	s_waitcnt lgkmcnt(2)
	s_add_u32 m0, s53, 0x400
	v_mfma_f32_16x16x32_bf16 v[144:147], v[16:19], v[192:195], v[144:147]
	global_load_lds_dwordx4 v205, s[22:23]
	v_mfma_f32_16x16x32_bf16 v[76:79], v[192:195], v[24:27], v[76:79]
	s_waitcnt lgkmcnt(1)
	s_add_u32 m0, s53, 0x800
	v_mfma_f32_16x16x32_bf16 v[92:95], v[0:3], v[196:199], v[92:95]
	global_load_lds_dwordx4 v206, s[22:23]
	v_mfma_f32_16x16x32_bf16 v[72:75], v[196:199], v[4:7], v[72:75]
	s_waitcnt lgkmcnt(0)
	s_add_u32 m0, s53, 0xc00
	v_mfma_f32_16x16x32_bf16 v[144:147], v[0:3], v[200:203], v[144:147]
	global_load_lds_dwordx4 v207, s[22:23]
	v_mfma_f32_16x16x32_bf16 v[76:79], v[200:203], v[4:7], v[76:79]
	s_waitcnt vmcnt(16)
	v_mov_b32_e32 v255, v88
	s_nop 7
	v_lshlrev_b32_e32 v242, 16, v186
	v_lshlrev_b32_e32 v243, 16, v188
	v_lshlrev_b32_e32 v244, 16, v185
	v_lshlrev_b32_e32 v245, 16, v89
	v_sub_f32_e32 v242, v242, v92
	v_sub_f32_e32 v243, v243, v93
	v_sub_f32_e32 v244, v244, v94
	v_sub_f32_e32 v245, v245, v95
	v_cvt_pk_bf16_f32 v242, v242, v243
	v_cvt_pk_bf16_f32 v243, v244, v245
	ds_write_b64 v247, v[242:243]
	v_lshlrev_b32_e32 v242, 16, v91
	v_lshlrev_b32_e32 v243, 16, v187
	v_lshlrev_b32_e32 v244, 16, v189
	v_lshlrev_b32_e32 v245, 16, v190
	v_sub_f32_e32 v242, v242, v144
	v_sub_f32_e32 v243, v243, v145
	v_sub_f32_e32 v244, v244, v146
	v_sub_f32_e32 v245, v245, v147
	v_cvt_pk_bf16_f32 v242, v242, v243
	v_cvt_pk_bf16_f32 v243, v244, v245
	ds_write_b64 v247, v[242:243] offset:2304
	global_load_ushort v186, v212, s[20:21] offset:0
	global_load_ushort v188, v212, s[20:21] offset:256
	global_load_ushort v185, v212, s[20:21] offset:512
	global_load_ushort v89, v212, s[20:21] offset:768
	global_load_ushort v91, v212, s[20:21] offset:32
	global_load_ushort v187, v212, s[20:21] offset:288
	global_load_ushort v189, v212, s[20:21] offset:544
	global_load_ushort v190, v212, s[20:21] offset:800
	global_load_dword v88, v113, s[46:47]
	s_waitcnt lgkmcnt(0)
	s_barrier
	s_waitcnt vmcnt(19)
	ds_read_b128 v[52:55], v221
	ds_read_b128 v[48:51], v222
	ds_read_b128 v[40:43], v217
	ds_read_b128 v[36:39], v220
	ds_read_b128 v[8:11], v217 offset:2048
	ds_read_b128 v[20:23], v220 offset:2048
	ds_read_b128 v[148:151], v248 offset:0
	ds_read_b128 v[192:195], v248 offset:2304
	ds_read_b128 v[196:199], v248 offset:64
	ds_read_b128 v[200:203], v248 offset:2368
	v_mul_f32_e32 v56, v56, v255
	v_mul_f32_e32 v57, v57, v255
	v_mul_f32_e32 v58, v58, v255
	v_mul_f32_e32 v59, v59, v255
	v_mul_f32_e32 v64, v64, v255
	v_mul_f32_e32 v65, v65, v255
	v_mul_f32_e32 v66, v66, v255
	v_mul_f32_e32 v67, v67, v255
	v_mul_f32_e32 v68, v68, v255
	v_mul_f32_e32 v69, v69, v255
	v_mul_f32_e32 v70, v70, v255
	v_mul_f32_e32 v71, v71, v255
	v_mul_f32_e32 v60, v60, v255
	v_mul_f32_e32 v61, v61, v255
	v_mul_f32_e32 v62, v62, v255
	v_mul_f32_e32 v63, v63, v255
	s_waitcnt lgkmcnt(4)
	s_waitcnt lgkmcnt(3)
	v_mfma_f32_16x16x32_bf16 v[72:75], v[148:151], v[52:55], v[72:75]
	s_waitcnt lgkmcnt(2)
	v_mfma_f32_16x16x32_bf16 v[76:79], v[192:195], v[52:55], v[76:79]
	s_waitcnt lgkmcnt(1)
	v_mfma_f32_16x16x32_bf16 v[72:75], v[196:199], v[48:51], v[72:75]
	s_waitcnt lgkmcnt(0)
	v_mfma_f32_16x16x32_bf16 v[76:79], v[200:203], v[48:51], v[76:79]
	s_mov_b32 m0, s54
	v_mfma_f32_16x16x32_bf16 v[56:59], v[40:43], v[148:151], v[56:59]
	global_load_lds_dwordx4 v210, s[20:21]
	v_mfma_f32_16x16x32_bf16 v[64:67], v[40:43], v[192:195], v[64:67]
	v_mfma_f32_16x16x32_bf16 v[56:59], v[36:39], v[196:199], v[56:59]
	global_load_lds_dwordx4 v210, s[20:21] offset:1024
	v_mfma_f32_16x16x32_bf16 v[64:67], v[36:39], v[200:203], v[64:67]
	v_mfma_f32_16x16x32_bf16 v[68:71], v[8:11], v[148:151], v[68:71]
	global_load_lds_dwordx4 v210, s[20:21] offset:2048
	v_mfma_f32_16x16x32_bf16 v[60:63], v[8:11], v[192:195], v[60:63]
	v_mfma_f32_16x16x32_bf16 v[68:71], v[20:23], v[196:199], v[68:71]
	global_load_lds_dwordx4 v210, s[20:21] offset:3072
	v_mfma_f32_16x16x32_bf16 v[60:63], v[20:23], v[200:203], v[60:63]
	s_mov_b32 m0, s55
	s_nop 0
	global_load_lds_dwordx4 v211, s[20:21]
	s_nop 0
	global_load_lds_dwordx4 v211, s[20:21] offset:1024
	s_nop 3
	global_store_dwordx4 v[86:87], v[72:75], off
	global_store_dwordx4 v[86:87], v[76:79], off offset:64
	s_nop 7
	v_cvt_pk_bf16_f32 v242, v56, v57
	v_cvt_pk_bf16_f32 v243, v58, v59
	ds_write_b64 v249, v[242:243]
	v_cvt_pk_bf16_f32 v242, v64, v65
	v_cvt_pk_bf16_f32 v243, v66, v67
	ds_write_b64 v249, v[242:243] offset:4352
	v_cvt_pk_bf16_f32 v242, v68, v69
	v_cvt_pk_bf16_f32 v243, v70, v71
	ds_write_b64 v249, v[242:243] offset:32
	v_cvt_pk_bf16_f32 v242, v60, v61
	v_cvt_pk_bf16_f32 v243, v62, v63
	ds_write_b64 v249, v[242:243] offset:4384
	v_lshl_add_u64 v[86:87], v[86:87], 0, s[50:51]
	s_add_u32 s20, s20, 0x12000
	s_addc_u32 s21, s21, 0
	s_add_u32 s22, s22, 0x12000
	s_addc_u32 s23, s23, 0
	s_add_u32 s46, s46, 4
	s_addc_u32 s47, s47, 0
	s_waitcnt lgkmcnt(0)
	s_barrier
	s_mov_b32 s1, 29

.LBB0_687:
	s_cmp_gt_i32 s63, 0x1ff
	v_lshlrev_b32_e32 v110, 2, v102
	v_lshlrev_b32_e32 v16, 2, v108
	v_lshlrev_b32_e32 v104, 12, v167
	s_cbranch_scc1 .LBB0_689
	v_readlane_b32 s4, v251, 6
	v_readlane_b32 s5, v251, 7
	v_readlane_b32 s6, v251, 0
	v_readlane_b32 s7, v251, 1
	v_readlane_b32 s8, v251, 48
	v_readlane_b32 s9, v251, 49
	s_lshr_b32 s10, s63, 6
	s_and_b32 s11, s63, 63
	s_lshr_b32 s0, s10, 1
	s_and_b32 s10, s10, 1
	s_add_u32 s4, s4, 0x2000000
	s_addc_u32 s5, s5, 0
	s_mul_i32 s0, s0, 0x200
	s_add_u32 s4, s4, s0
	s_addc_u32 s5, s5, 0
	s_add_u32 s6, s6, s0
	s_addc_u32 s7, s7, 0
	s_add_u32 s8, s8, 0x4000000
	s_addc_u32 s9, s9, 0
	s_lshl_b32 s12, s11, 4
	s_mul_i32 s13, s12, 0x800
	s_lshl_b32 s14, s12, 2
	s_lshl_b32 s15, s10, 6
	v_and_b32_e32 v93, 63, v162
	v_lshrrev_b32_e32 v94, 6, v162
	v_and_b32_e32 v95, 15, v93
	v_lshrrev_b32_e32 v93, 4, v93
	v_lshl_add_u32 v94, v94, 4, s15
	v_add_u32_e32 v19, v94, v95
	v_mul_u32_u24_e32 v19, 0x800, v19
	v_lshl_add_u32 v19, v93, 5, v19
	v_mul_u32_u24_e32 v88, 0x800, v95
	v_lshl_add_u32 v88, v93, 5, v88
	v_add_u32_e32 v88, s13, v88
	v_lshl_add_u32 v94, v93, 2, v94
	v_mul_u32_u24_e32 v89, 0x1000, v94
	v_lshl_add_u32 v89, v95, 2, v89
	v_add_u32_e32 v89, s14, v89
	v_add_u32_e32 v90, 0x1000, v89
	v_add_u32_e32 v91, 0x1000, v90
	v_add_u32_e32 v92, 0x1000, v91
	v_mov_b32_e32 v20, 0
	v_mov_b32_e32 v21, 0
	v_mov_b32_e32 v22, 0
	v_mov_b32_e32 v23, 0
	global_load_dwordx4 v[24:27], v19, s[4:5] offset:0
	global_load_dwordx4 v[32:35], v88, s[6:7] offset:0
	global_load_dwordx4 v[28:31], v19, s[4:5] offset:16
	global_load_dwordx4 v[36:39], v88, s[6:7] offset:16
	global_load_dwordx4 v[40:43], v19, s[4:5] offset:128
	global_load_dwordx4 v[48:51], v88, s[6:7] offset:128
	global_load_dwordx4 v[44:47], v19, s[4:5] offset:144
	global_load_dwordx4 v[52:55], v88, s[6:7] offset:144
	global_load_dwordx4 v[56:59], v19, s[4:5] offset:256
	global_load_dwordx4 v[64:67], v88, s[6:7] offset:256
	global_load_dwordx4 v[60:63], v19, s[4:5] offset:272
	global_load_dwordx4 v[68:71], v88, s[6:7] offset:272
	global_load_dwordx4 v[72:75], v19, s[4:5] offset:384
	global_load_dwordx4 v[80:83], v88, s[6:7] offset:384
	global_load_dwordx4 v[76:79], v19, s[4:5] offset:400
	global_load_dwordx4 v[84:87], v88, s[6:7] offset:400
	s_waitcnt vmcnt(14)
	v_mfma_f32_16x16x32_bf16 v[20:23], v[24:27], v[32:35], v[20:23]
	s_waitcnt vmcnt(12)
	v_mfma_f32_16x16x32_bf16 v[20:23], v[28:31], v[36:39], v[20:23]
	s_waitcnt vmcnt(10)
	v_mfma_f32_16x16x32_bf16 v[20:23], v[40:43], v[48:51], v[20:23]
	s_waitcnt vmcnt(8)
	v_mfma_f32_16x16x32_bf16 v[20:23], v[44:47], v[52:55], v[20:23]
	s_waitcnt vmcnt(6)
	v_mfma_f32_16x16x32_bf16 v[20:23], v[56:59], v[64:67], v[20:23]
	s_waitcnt vmcnt(4)
	v_mfma_f32_16x16x32_bf16 v[20:23], v[60:63], v[68:71], v[20:23]
	s_waitcnt vmcnt(2)
	v_mfma_f32_16x16x32_bf16 v[20:23], v[72:75], v[80:83], v[20:23]
	s_waitcnt vmcnt(0)
	v_mfma_f32_16x16x32_bf16 v[20:23], v[76:79], v[84:87], v[20:23]
	s_nop 7
	s_nop 7
	global_atomic_add_f32 v89, v20, s[8:9]
	global_atomic_add_f32 v90, v21, s[8:9]
	global_atomic_add_f32 v91, v22, s[8:9]
	global_atomic_add_f32 v92, v23, s[8:9]

.LBB0_925:
	s_cmpk_gt_i32 s63, 0x1ff
	s_cbranch_scc1 .LBB0_927
	s_mov_b64 s[4:5], s[80:81]
	v_readlane_b32 s6, v251, 4
	v_readlane_b32 s7, v251, 5
	v_readlane_b32 s8, v251, 48
	v_readlane_b32 s9, v251, 49
	s_lshr_b32 s10, s63, 6
	s_and_b32 s11, s63, 63
	s_lshr_b32 s0, s10, 1
	s_and_b32 s10, s10, 1
	s_add_u32 s4, s4, 0x5800000
	s_addc_u32 s5, s5, 0
	s_mul_i32 s0, s0, 0x580
	s_add_u32 s4, s4, s0
	s_addc_u32 s5, s5, 0
	s_add_u32 s6, s6, s0
	s_addc_u32 s7, s7, 0
	s_add_u32 s8, s8, 0x4000000
	s_addc_u32 s9, s9, 0
	s_lshl_b32 s12, s11, 4
	s_mul_i32 s13, s12, 0x1600
	s_lshl_b32 s14, s12, 2
	s_lshl_b32 s15, s10, 6
	v_mbcnt_lo_u32_b32 v93, -1, 0
	v_mbcnt_hi_u32_b32 v93, -1, v93
	v_lshrrev_b32_e32 v94, 3, v96
	v_and_b32_e32 v95, 15, v93
	v_lshrrev_b32_e32 v93, 4, v93
	v_lshl_add_u32 v94, v94, 4, s15
	v_add_u32_e32 v19, v94, v95
	v_mul_u32_u24_e32 v19, 0x1600, v19
	v_lshl_add_u32 v19, v93, 5, v19
	v_mul_u32_u24_e32 v88, 0x1600, v95
	v_lshl_add_u32 v88, v93, 5, v88
	v_add_u32_e32 v88, s13, v88
	v_lshl_add_u32 v94, v93, 2, v94
	v_mul_u32_u24_e32 v89, 0x1000, v94
	v_lshl_add_u32 v89, v95, 2, v89
	v_add_u32_e32 v89, s14, v89
	v_add_u32_e32 v90, 0x1000, v89
	v_add_u32_e32 v91, 0x1000, v90
	v_add_u32_e32 v92, 0x1000, v91
	v_mov_b32_e32 v20, 0
	v_mov_b32_e32 v21, 0
	v_mov_b32_e32 v22, 0
	v_mov_b32_e32 v23, 0
	global_load_dwordx4 v[24:27], v19, s[4:5] offset:0
	global_load_dwordx4 v[32:35], v88, s[6:7] offset:0
	global_load_dwordx4 v[28:31], v19, s[4:5] offset:16
	global_load_dwordx4 v[36:39], v88, s[6:7] offset:16
	global_load_dwordx4 v[40:43], v19, s[4:5] offset:128
	global_load_dwordx4 v[48:51], v88, s[6:7] offset:128
	global_load_dwordx4 v[44:47], v19, s[4:5] offset:144
	global_load_dwordx4 v[52:55], v88, s[6:7] offset:144
	global_load_dwordx4 v[56:59], v19, s[4:5] offset:256
	global_load_dwordx4 v[64:67], v88, s[6:7] offset:256
	global_load_dwordx4 v[60:63], v19, s[4:5] offset:272
	global_load_dwordx4 v[68:71], v88, s[6:7] offset:272
	global_load_dwordx4 v[72:75], v19, s[4:5] offset:384
	global_load_dwordx4 v[80:83], v88, s[6:7] offset:384
	global_load_dwordx4 v[76:79], v19, s[4:5] offset:400
	global_load_dwordx4 v[84:87], v88, s[6:7] offset:400
	global_load_dwordx4 v[114:117], v19, s[4:5] offset:512
	global_load_dwordx4 v[122:125], v88, s[6:7] offset:512
	global_load_dwordx4 v[118:121], v19, s[4:5] offset:528
	global_load_dwordx4 v[126:129], v88, s[6:7] offset:528
	global_load_dwordx4 v[134:137], v19, s[4:5] offset:640
	global_load_dwordx4 v[142:145], v88, s[6:7] offset:640
	global_load_dwordx4 v[138:141], v19, s[4:5] offset:656
	global_load_dwordx4 v[146:149], v88, s[6:7] offset:656
	s_waitcnt vmcnt(22)
	v_mfma_f32_16x16x32_bf16 v[20:23], v[24:27], v[32:35], v[20:23]
	s_waitcnt vmcnt(20)
	v_mfma_f32_16x16x32_bf16 v[20:23], v[28:31], v[36:39], v[20:23]
	s_nop 1
	global_load_dwordx4 v[24:27], v19, s[4:5] offset:768
	global_load_dwordx4 v[32:35], v88, s[6:7] offset:768
	global_load_dwordx4 v[28:31], v19, s[4:5] offset:784
	global_load_dwordx4 v[36:39], v88, s[6:7] offset:784
	s_waitcnt vmcnt(22)
	v_mfma_f32_16x16x32_bf16 v[20:23], v[40:43], v[48:51], v[20:23]
	s_waitcnt vmcnt(20)
	v_mfma_f32_16x16x32_bf16 v[20:23], v[44:47], v[52:55], v[20:23]
	s_nop 1
	global_load_dwordx4 v[40:43], v19, s[4:5] offset:896
	global_load_dwordx4 v[48:51], v88, s[6:7] offset:896
	global_load_dwordx4 v[44:47], v19, s[4:5] offset:912
	global_load_dwordx4 v[52:55], v88, s[6:7] offset:912
	s_waitcnt vmcnt(22)
	v_mfma_f32_16x16x32_bf16 v[20:23], v[56:59], v[64:67], v[20:23]
	s_waitcnt vmcnt(20)
	v_mfma_f32_16x16x32_bf16 v[20:23], v[60:63], v[68:71], v[20:23]
	s_nop 1
	global_load_dwordx4 v[56:59], v19, s[4:5] offset:1024
	global_load_dwordx4 v[64:67], v88, s[6:7] offset:1024
	global_load_dwordx4 v[60:63], v19, s[4:5] offset:1040
	global_load_dwordx4 v[68:71], v88, s[6:7] offset:1040
	s_waitcnt vmcnt(22)
	v_mfma_f32_16x16x32_bf16 v[20:23], v[72:75], v[80:83], v[20:23]
	s_waitcnt vmcnt(20)
	v_mfma_f32_16x16x32_bf16 v[20:23], v[76:79], v[84:87], v[20:23]
	s_nop 1
	global_load_dwordx4 v[72:75], v19, s[4:5] offset:1152
	global_load_dwordx4 v[80:83], v88, s[6:7] offset:1152
	global_load_dwordx4 v[76:79], v19, s[4:5] offset:1168
	global_load_dwordx4 v[84:87], v88, s[6:7] offset:1168
	s_waitcnt vmcnt(22)
	v_mfma_f32_16x16x32_bf16 v[20:23], v[114:117], v[122:125], v[20:23]
	s_waitcnt vmcnt(20)
	v_mfma_f32_16x16x32_bf16 v[20:23], v[118:121], v[126:129], v[20:23]
	s_nop 1
	global_load_dwordx4 v[114:117], v19, s[4:5] offset:1280
	global_load_dwordx4 v[122:125], v88, s[6:7] offset:1280
	global_load_dwordx4 v[118:121], v19, s[4:5] offset:1296
	global_load_dwordx4 v[126:129], v88, s[6:7] offset:1296
	s_waitcnt vmcnt(22)
	v_mfma_f32_16x16x32_bf16 v[20:23], v[134:137], v[142:145], v[20:23]
	s_waitcnt vmcnt(20)
	v_mfma_f32_16x16x32_bf16 v[20:23], v[138:141], v[146:149], v[20:23]
	s_waitcnt vmcnt(18)
	v_mfma_f32_16x16x32_bf16 v[20:23], v[24:27], v[32:35], v[20:23]
	s_waitcnt vmcnt(16)
	v_mfma_f32_16x16x32_bf16 v[20:23], v[28:31], v[36:39], v[20:23]
	s_waitcnt vmcnt(14)
	v_mfma_f32_16x16x32_bf16 v[20:23], v[40:43], v[48:51], v[20:23]
	s_waitcnt vmcnt(12)
	v_mfma_f32_16x16x32_bf16 v[20:23], v[44:47], v[52:55], v[20:23]
	s_waitcnt vmcnt(10)
	v_mfma_f32_16x16x32_bf16 v[20:23], v[56:59], v[64:67], v[20:23]
	s_waitcnt vmcnt(8)
	v_mfma_f32_16x16x32_bf16 v[20:23], v[60:63], v[68:71], v[20:23]
	s_waitcnt vmcnt(6)
	v_mfma_f32_16x16x32_bf16 v[20:23], v[72:75], v[80:83], v[20:23]
	s_waitcnt vmcnt(4)
	v_mfma_f32_16x16x32_bf16 v[20:23], v[76:79], v[84:87], v[20:23]
	s_waitcnt vmcnt(2)
	v_mfma_f32_16x16x32_bf16 v[20:23], v[114:117], v[122:125], v[20:23]
	s_waitcnt vmcnt(0)
	v_mfma_f32_16x16x32_bf16 v[20:23], v[118:121], v[126:129], v[20:23]
	s_nop 7
	s_nop 7
	global_atomic_add_f32 v89, v20, s[8:9]
	global_atomic_add_f32 v90, v21, s[8:9]
	global_atomic_add_f32 v91, v22, s[8:9]
	global_atomic_add_f32 v92, v23, s[8:9]

	.amdhsa_kernel _Z14fwd_megakernel6Params
		.amdhsa_group_segment_fixed_size 78080
		.amdhsa_private_segment_fixed_size 0
		.amdhsa_kernarg_size 696
		.amdhsa_user_sgpr_count 2
		.amdhsa_user_sgpr_dispatch_ptr 0
		.amdhsa_user_sgpr_queue_ptr 0
		.amdhsa_user_sgpr_kernarg_segment_ptr 1
		.amdhsa_user_sgpr_dispatch_id 0
		.amdhsa_user_sgpr_kernarg_preload_length 0
		.amdhsa_user_sgpr_kernarg_preload_offset 0
		.amdhsa_user_sgpr_private_segment_size 0
		.amdhsa_uses_dynamic_stack 0
		.amdhsa_enable_private_segment 0
		.amdhsa_system_sgpr_workgroup_id_x 1
		.amdhsa_system_sgpr_workgroup_id_y 0
		.amdhsa_system_sgpr_workgroup_id_z 0
		.amdhsa_system_sgpr_workgroup_info 0
		.amdhsa_system_vgpr_workitem_id 2
		.amdhsa_next_free_vgpr 256
		.amdhsa_next_free_sgpr 102
		.amdhsa_accum_offset 256
		.amdhsa_reserve_vcc 1
		.amdhsa_float_round_mode_32 0
		.amdhsa_float_round_mode_16_64 0
		.amdhsa_float_denorm_mode_32 3
		.amdhsa_float_denorm_mode_16_64 3
		.amdhsa_dx10_clamp 1
		.amdhsa_ieee_mode 1
		.amdhsa_fp16_overflow 0
		.amdhsa_tg_split 0
		.amdhsa_exception_fp_ieee_invalid_op 0
		.amdhsa_exception_fp_denorm_src 0
		.amdhsa_exception_fp_ieee_div_zero 0
		.amdhsa_exception_fp_ieee_overflow 0
		.amdhsa_exception_fp_ieee_underflow 0
		.amdhsa_exception_fp_ieee_inexact 0
		.amdhsa_exception_int_div_zero 0
	.end_amdhsa_kernel

amdhsa.kernels:
  - .agpr_count:     0
    .args:
      - .offset:         0
        .size:           440
        .value_kind:     by_value
      - .offset:         440
        .size:           4
        .value_kind:     hidden_block_count_x
      - .offset:         444
        .size:           4
        .value_kind:     hidden_block_count_y
      - .offset:         448
        .size:           4
        .value_kind:     hidden_block_count_z
      - .offset:         452
        .size:           2
        .value_kind:     hidden_group_size_x
      - .offset:         454
        .size:           2
        .value_kind:     hidden_group_size_y
      - .offset:         456
        .size:           2
        .value_kind:     hidden_group_size_z
      - .offset:         458
        .size:           2
        .value_kind:     hidden_remainder_x
      - .offset:         460
        .size:           2
        .value_kind:     hidden_remainder_y
      - .offset:         462
        .size:           2
        .value_kind:     hidden_remainder_z
      - .offset:         480
        .size:           8
        .value_kind:     hidden_global_offset_x
      - .offset:         488
        .size:           8
        .value_kind:     hidden_global_offset_y
      - .offset:         496
        .size:           8
        .value_kind:     hidden_global_offset_z
      - .offset:         504
        .size:           2
        .value_kind:     hidden_grid_dims
      - .offset:         528
        .size:           8
        .value_kind:     hidden_multigrid_sync_arg
    .group_segment_fixed_size: 78080
    .kernarg_segment_align: 8
    .kernarg_segment_size: 696
    .language:       OpenCL C
    .language_version:
      - 2
      - 0
    .max_flat_workgroup_size: 256
    .name:           _Z14fwd_megakernel6Params
    .private_segment_fixed_size: 0
    .sgpr_count:     108
    .sgpr_spill_count: 176
    .symbol:         _Z14fwd_megakernel6Params.kd
    .uniform_work_group_size: 1
    .uses_dynamic_stack: false
    .vgpr_count:     256
    .vgpr_spill_count: 0
    .wavefront_size: 64
